# v91 + prologue silu(c) staging: 18 conditioning loads per thread issued together before the silu+LDS writes (were 18 serialized round trips)
# baseline (speedup 1.0000x reference)
.LBB0_792:
	s_movk_i32 s6, 0x8000
	s_mov_b32 s7, -1
	v_lshl_add_u64 v[4:5], v[160:161], 2, s[62:63]
	v_lshl_add_u64 v[4:5], v[4:5], 0, s[6:7]
	v_cmp_gt_i32_e32 vcc, s20, v160
	s_nop 1
	v_cndmask_b32_e32 v5, v5, v1, vcc
	v_cndmask_b32_e32 v4, v4, v0, vcc
	s_nop 1
	global_load_dword v206, v[4:5], off
	v_add_u32_e32 v160, 0x200, v160
	v_lshl_add_u64 v[0:1], v[0:1], 0, s[8:9]
	v_lshl_add_u64 v[4:5], v[160:161], 2, s[62:63]
	v_lshl_add_u64 v[4:5], v[4:5], 0, s[6:7]
	v_cmp_gt_i32_e32 vcc, s20, v160
	s_nop 1
	v_cndmask_b32_e32 v5, v5, v1, vcc
	v_cndmask_b32_e32 v4, v4, v0, vcc
	s_nop 1
	global_load_dword v207, v[4:5], off
	v_add_u32_e32 v160, 0x200, v160
	v_lshl_add_u64 v[0:1], v[0:1], 0, s[8:9]
	v_lshl_add_u64 v[4:5], v[160:161], 2, s[62:63]
	v_lshl_add_u64 v[4:5], v[4:5], 0, s[6:7]
	v_cmp_gt_i32_e32 vcc, s20, v160
	s_nop 1
	v_cndmask_b32_e32 v5, v5, v1, vcc
	v_cndmask_b32_e32 v4, v4, v0, vcc
	s_nop 1
	global_load_dword v208, v[4:5], off
	v_add_u32_e32 v160, 0x200, v160
	v_lshl_add_u64 v[0:1], v[0:1], 0, s[8:9]
	v_lshl_add_u64 v[4:5], v[160:161], 2, s[62:63]
	v_lshl_add_u64 v[4:5], v[4:5], 0, s[6:7]
	v_cmp_gt_i32_e32 vcc, s20, v160
	s_nop 1
	v_cndmask_b32_e32 v5, v5, v1, vcc
	v_cndmask_b32_e32 v4, v4, v0, vcc
	s_nop 1
	global_load_dword v209, v[4:5], off
	v_add_u32_e32 v160, 0x200, v160
	v_lshl_add_u64 v[0:1], v[0:1], 0, s[8:9]
	v_lshl_add_u64 v[4:5], v[160:161], 2, s[62:63]
	v_lshl_add_u64 v[4:5], v[4:5], 0, s[6:7]
	v_cmp_gt_i32_e32 vcc, s20, v160
	s_nop 1
	v_cndmask_b32_e32 v5, v5, v1, vcc
	v_cndmask_b32_e32 v4, v4, v0, vcc
	s_nop 1
	global_load_dword v210, v[4:5], off
	v_add_u32_e32 v160, 0x200, v160
	v_lshl_add_u64 v[0:1], v[0:1], 0, s[8:9]
	v_lshl_add_u64 v[4:5], v[160:161], 2, s[62:63]
	v_lshl_add_u64 v[4:5], v[4:5], 0, s[6:7]
	v_cmp_gt_i32_e32 vcc, s20, v160
	s_nop 1
	v_cndmask_b32_e32 v5, v5, v1, vcc
	v_cndmask_b32_e32 v4, v4, v0, vcc
	s_nop 1
	global_load_dword v211, v[4:5], off
	v_add_u32_e32 v160, 0x200, v160
	v_lshl_add_u64 v[0:1], v[0:1], 0, s[8:9]
	v_lshl_add_u64 v[4:5], v[160:161], 2, s[62:63]
	v_lshl_add_u64 v[4:5], v[4:5], 0, s[6:7]
	v_cmp_gt_i32_e32 vcc, s20, v160
	s_nop 1
	v_cndmask_b32_e32 v5, v5, v1, vcc
	v_cndmask_b32_e32 v4, v4, v0, vcc
	s_nop 1
	global_load_dword v212, v[4:5], off
	v_add_u32_e32 v160, 0x200, v160
	v_lshl_add_u64 v[0:1], v[0:1], 0, s[8:9]
	v_lshl_add_u64 v[4:5], v[160:161], 2, s[62:63]
	v_lshl_add_u64 v[4:5], v[4:5], 0, s[6:7]
	v_cmp_gt_i32_e32 vcc, s20, v160
	s_nop 1
	v_cndmask_b32_e32 v5, v5, v1, vcc
	v_cndmask_b32_e32 v4, v4, v0, vcc
	s_nop 1
	global_load_dword v213, v[4:5], off
	v_add_u32_e32 v160, 0x200, v160
	v_lshl_add_u64 v[0:1], v[0:1], 0, s[8:9]
	v_lshl_add_u64 v[4:5], v[160:161], 2, s[62:63]
	v_lshl_add_u64 v[4:5], v[4:5], 0, s[6:7]
	v_cmp_gt_i32_e32 vcc, s20, v160
	s_nop 1
	v_cndmask_b32_e32 v5, v5, v1, vcc
	v_cndmask_b32_e32 v4, v4, v0, vcc
	s_nop 1
	global_load_dword v214, v[4:5], off
	v_add_u32_e32 v160, 0x200, v160
	v_lshl_add_u64 v[0:1], v[0:1], 0, s[8:9]
	v_lshl_add_u64 v[4:5], v[160:161], 2, s[62:63]
	v_lshl_add_u64 v[4:5], v[4:5], 0, s[6:7]
	v_cmp_gt_i32_e32 vcc, s20, v160
	s_nop 1
	v_cndmask_b32_e32 v5, v5, v1, vcc
	v_cndmask_b32_e32 v4, v4, v0, vcc
	s_nop 1
	global_load_dword v215, v[4:5], off
	v_add_u32_e32 v160, 0x200, v160
	v_lshl_add_u64 v[0:1], v[0:1], 0, s[8:9]
	v_lshl_add_u64 v[4:5], v[160:161], 2, s[62:63]
	v_lshl_add_u64 v[4:5], v[4:5], 0, s[6:7]
	v_cmp_gt_i32_e32 vcc, s20, v160
	s_nop 1
	v_cndmask_b32_e32 v5, v5, v1, vcc
	v_cndmask_b32_e32 v4, v4, v0, vcc
	s_nop 1
	global_load_dword v216, v[4:5], off
	v_add_u32_e32 v160, 0x200, v160
	v_lshl_add_u64 v[0:1], v[0:1], 0, s[8:9]
	v_lshl_add_u64 v[4:5], v[160:161], 2, s[62:63]
	v_lshl_add_u64 v[4:5], v[4:5], 0, s[6:7]
	v_cmp_gt_i32_e32 vcc, s20, v160
	s_nop 1
	v_cndmask_b32_e32 v5, v5, v1, vcc
	v_cndmask_b32_e32 v4, v4, v0, vcc
	s_nop 1
	global_load_dword v217, v[4:5], off
	v_add_u32_e32 v160, 0x200, v160
	v_lshl_add_u64 v[0:1], v[0:1], 0, s[8:9]
	v_lshl_add_u64 v[4:5], v[160:161], 2, s[62:63]
	v_lshl_add_u64 v[4:5], v[4:5], 0, s[6:7]
	v_cmp_gt_i32_e32 vcc, s20, v160
	s_nop 1
	v_cndmask_b32_e32 v5, v5, v1, vcc
	v_cndmask_b32_e32 v4, v4, v0, vcc
	s_nop 1
	global_load_dword v218, v[4:5], off
	v_add_u32_e32 v160, 0x200, v160
	v_lshl_add_u64 v[0:1], v[0:1], 0, s[8:9]
	v_lshl_add_u64 v[4:5], v[160:161], 2, s[62:63]
	v_lshl_add_u64 v[4:5], v[4:5], 0, s[6:7]
	v_cmp_gt_i32_e32 vcc, s20, v160
	s_nop 1
	v_cndmask_b32_e32 v5, v5, v1, vcc
	v_cndmask_b32_e32 v4, v4, v0, vcc
	s_nop 1
	global_load_dword v219, v[4:5], off
	v_add_u32_e32 v160, 0x200, v160
	v_lshl_add_u64 v[0:1], v[0:1], 0, s[8:9]
	v_lshl_add_u64 v[4:5], v[160:161], 2, s[62:63]
	v_lshl_add_u64 v[4:5], v[4:5], 0, s[6:7]
	v_cmp_gt_i32_e32 vcc, s20, v160
	s_nop 1
	v_cndmask_b32_e32 v5, v5, v1, vcc
	v_cndmask_b32_e32 v4, v4, v0, vcc
	s_nop 1
	global_load_dword v220, v[4:5], off
	v_add_u32_e32 v160, 0x200, v160
	v_lshl_add_u64 v[0:1], v[0:1], 0, s[8:9]
	v_lshl_add_u64 v[4:5], v[160:161], 2, s[62:63]
	v_lshl_add_u64 v[4:5], v[4:5], 0, s[6:7]
	v_cmp_gt_i32_e32 vcc, s20, v160
	s_nop 1
	v_cndmask_b32_e32 v5, v5, v1, vcc
	v_cndmask_b32_e32 v4, v4, v0, vcc
	s_nop 1
	global_load_dword v221, v[4:5], off
	v_add_u32_e32 v160, 0x200, v160
	v_lshl_add_u64 v[0:1], v[0:1], 0, s[8:9]
	v_lshl_add_u64 v[4:5], v[160:161], 2, s[62:63]
	v_lshl_add_u64 v[4:5], v[4:5], 0, s[6:7]
	v_cmp_gt_i32_e32 vcc, s20, v160
	s_nop 1
	v_cndmask_b32_e32 v5, v5, v1, vcc
	v_cndmask_b32_e32 v4, v4, v0, vcc
	s_nop 1
	global_load_dword v222, v[4:5], off
	v_add_u32_e32 v160, 0x200, v160
	v_lshl_add_u64 v[0:1], v[0:1], 0, s[8:9]
	v_lshl_add_u64 v[4:5], v[160:161], 2, s[62:63]
	v_lshl_add_u64 v[4:5], v[4:5], 0, s[6:7]
	v_cmp_gt_i32_e32 vcc, s20, v160
	s_nop 1
	v_cndmask_b32_e32 v5, v5, v1, vcc
	v_cndmask_b32_e32 v4, v4, v0, vcc
	s_nop 1
	global_load_dword v223, v[4:5], off
	v_add_u32_e32 v160, 0x200, v160
	v_lshl_add_u64 v[0:1], v[0:1], 0, s[8:9]
	s_waitcnt vmcnt(17)
	v_mul_f32_e32 v5, 0xbfb8aa3b, v206
	v_exp_f32_e32 v5, v5
	s_nop 0
	v_add_f32_e32 v5, 1.0, v5
	v_rcp_f32_e32 v5, v5
	s_nop 0
	v_mul_f32_e32 v3, v206, v5
	ds_write_b32 v2, v3
	v_add_u32_e32 v2, 0x800, v2
	s_waitcnt vmcnt(16)
	v_mul_f32_e32 v5, 0xbfb8aa3b, v207
	v_exp_f32_e32 v5, v5
	s_nop 0
	v_add_f32_e32 v5, 1.0, v5
	v_rcp_f32_e32 v5, v5
	s_nop 0
	v_mul_f32_e32 v3, v207, v5
	ds_write_b32 v2, v3
	v_add_u32_e32 v2, 0x800, v2
	s_waitcnt vmcnt(15)
	v_mul_f32_e32 v5, 0xbfb8aa3b, v208
	v_exp_f32_e32 v5, v5
	s_nop 0
	v_add_f32_e32 v5, 1.0, v5
	v_rcp_f32_e32 v5, v5
	s_nop 0
	v_mul_f32_e32 v3, v208, v5
	ds_write_b32 v2, v3
	v_add_u32_e32 v2, 0x800, v2
	s_waitcnt vmcnt(14)
	v_mul_f32_e32 v5, 0xbfb8aa3b, v209
	v_exp_f32_e32 v5, v5
	s_nop 0
	v_add_f32_e32 v5, 1.0, v5
	v_rcp_f32_e32 v5, v5
	s_nop 0
	v_mul_f32_e32 v3, v209, v5
	ds_write_b32 v2, v3
	v_add_u32_e32 v2, 0x800, v2
	s_waitcnt vmcnt(13)
	v_mul_f32_e32 v5, 0xbfb8aa3b, v210
	v_exp_f32_e32 v5, v5
	s_nop 0
	v_add_f32_e32 v5, 1.0, v5
	v_rcp_f32_e32 v5, v5
	s_nop 0
	v_mul_f32_e32 v3, v210, v5
	ds_write_b32 v2, v3
	v_add_u32_e32 v2, 0x800, v2
	s_waitcnt vmcnt(12)
	v_mul_f32_e32 v5, 0xbfb8aa3b, v211
	v_exp_f32_e32 v5, v5
	s_nop 0
	v_add_f32_e32 v5, 1.0, v5
	v_rcp_f32_e32 v5, v5
	s_nop 0
	v_mul_f32_e32 v3, v211, v5
	ds_write_b32 v2, v3
	v_add_u32_e32 v2, 0x800, v2
	s_waitcnt vmcnt(11)
	v_mul_f32_e32 v5, 0xbfb8aa3b, v212
	v_exp_f32_e32 v5, v5
	s_nop 0
	v_add_f32_e32 v5, 1.0, v5
	v_rcp_f32_e32 v5, v5
	s_nop 0
	v_mul_f32_e32 v3, v212, v5
	ds_write_b32 v2, v3
	v_add_u32_e32 v2, 0x800, v2
	s_waitcnt vmcnt(10)
	v_mul_f32_e32 v5, 0xbfb8aa3b, v213
	v_exp_f32_e32 v5, v5
	s_nop 0
	v_add_f32_e32 v5, 1.0, v5
	v_rcp_f32_e32 v5, v5
	s_nop 0
	v_mul_f32_e32 v3, v213, v5
	ds_write_b32 v2, v3
	v_add_u32_e32 v2, 0x800, v2
	s_waitcnt vmcnt(9)
	v_mul_f32_e32 v5, 0xbfb8aa3b, v214
	v_exp_f32_e32 v5, v5
	s_nop 0
	v_add_f32_e32 v5, 1.0, v5
	v_rcp_f32_e32 v5, v5
	s_nop 0
	v_mul_f32_e32 v3, v214, v5
	ds_write_b32 v2, v3
	v_add_u32_e32 v2, 0x800, v2
	s_waitcnt vmcnt(8)
	v_mul_f32_e32 v5, 0xbfb8aa3b, v215
	v_exp_f32_e32 v5, v5
	s_nop 0
	v_add_f32_e32 v5, 1.0, v5
	v_rcp_f32_e32 v5, v5
	s_nop 0
	v_mul_f32_e32 v3, v215, v5
	ds_write_b32 v2, v3
	v_add_u32_e32 v2, 0x800, v2
	s_waitcnt vmcnt(7)
	v_mul_f32_e32 v5, 0xbfb8aa3b, v216
	v_exp_f32_e32 v5, v5
	s_nop 0
	v_add_f32_e32 v5, 1.0, v5
	v_rcp_f32_e32 v5, v5
	s_nop 0
	v_mul_f32_e32 v3, v216, v5
	ds_write_b32 v2, v3
	v_add_u32_e32 v2, 0x800, v2
	s_waitcnt vmcnt(6)
	v_mul_f32_e32 v5, 0xbfb8aa3b, v217
	v_exp_f32_e32 v5, v5
	s_nop 0
	v_add_f32_e32 v5, 1.0, v5
	v_rcp_f32_e32 v5, v5
	s_nop 0
	v_mul_f32_e32 v3, v217, v5
	ds_write_b32 v2, v3
	v_add_u32_e32 v2, 0x800, v2
	s_waitcnt vmcnt(5)
	v_mul_f32_e32 v5, 0xbfb8aa3b, v218
	v_exp_f32_e32 v5, v5
	s_nop 0
	v_add_f32_e32 v5, 1.0, v5
	v_rcp_f32_e32 v5, v5
	s_nop 0
	v_mul_f32_e32 v3, v218, v5
	ds_write_b32 v2, v3
	v_add_u32_e32 v2, 0x800, v2
	s_waitcnt vmcnt(4)
	v_mul_f32_e32 v5, 0xbfb8aa3b, v219
	v_exp_f32_e32 v5, v5
	s_nop 0
	v_add_f32_e32 v5, 1.0, v5
	v_rcp_f32_e32 v5, v5
	s_nop 0
	v_mul_f32_e32 v3, v219, v5
	ds_write_b32 v2, v3
	v_add_u32_e32 v2, 0x800, v2
	s_waitcnt vmcnt(3)
	v_mul_f32_e32 v5, 0xbfb8aa3b, v220
	v_exp_f32_e32 v5, v5
	s_nop 0
	v_add_f32_e32 v5, 1.0, v5
	v_rcp_f32_e32 v5, v5
	s_nop 0
	v_mul_f32_e32 v3, v220, v5
	ds_write_b32 v2, v3
	v_add_u32_e32 v2, 0x800, v2
	s_waitcnt vmcnt(2)
	v_mul_f32_e32 v5, 0xbfb8aa3b, v221
	v_exp_f32_e32 v5, v5
	s_nop 0
	v_add_f32_e32 v5, 1.0, v5
	v_rcp_f32_e32 v5, v5
	s_nop 0
	v_mul_f32_e32 v3, v221, v5
	ds_write_b32 v2, v3
	v_add_u32_e32 v2, 0x800, v2
	s_waitcnt vmcnt(1)
	v_mul_f32_e32 v5, 0xbfb8aa3b, v222
	v_exp_f32_e32 v5, v5
	s_nop 0
	v_add_f32_e32 v5, 1.0, v5
	v_rcp_f32_e32 v5, v5
	s_nop 0
	v_mul_f32_e32 v3, v222, v5
	ds_write_b32 v2, v3
	v_add_u32_e32 v2, 0x800, v2
	s_waitcnt vmcnt(0)
	v_mul_f32_e32 v5, 0xbfb8aa3b, v223
	v_exp_f32_e32 v5, v5
	s_nop 0
	v_add_f32_e32 v5, 1.0, v5
	v_rcp_f32_e32 v5, v5
	s_nop 0
	v_mul_f32_e32 v3, v223, v5
	ds_write_b32 v2, v3
	v_add_u32_e32 v2, 0x800, v2
